# P1: non-temporal hint on the streaming x loads (x is read once here; keeps the freshly written H resident for the in-proj GEMM)
# speedup vs baseline: 1.0145x; 1.0145x over previous
.LBB0_274:
	s_or_b64 exec, exec, s[0:1]
	v_ashrrev_i32_e32 v68, 6, v66
	v_ashrrev_i32_e32 v69, 31, v68
	v_and_b32_e32 v67, 63, v66
	v_lshlrev_b64 v[2:3], 12, v[68:69]
	v_lshl_add_u64 v[2:3], s[18:19], 0, v[2:3]
	v_lshlrev_b32_e32 v146, 4, v67
	v_lshl_add_u64 v[6:7], v[2:3], 0, v[146:147]
	s_waitcnt lgkmcnt(0)
	s_barrier
	global_load_dwordx4 v[2:5], v[6:7], off nt
	global_load_dwordx4 v[14:17], v[6:7], off offset:1024 nt
	global_load_dwordx4 v[18:21], v[6:7], off offset:2048 nt
	global_load_dwordx4 v[22:25], v[6:7], off offset:3072 nt
	v_and_b32_e32 v6, 64, v1
	s_waitcnt vmcnt(19)
	v_add_u32_e32 v39, 64, v6
	v_mul_lo_u32 v6, v68, s79
	v_add_u32_e32 v40, 0, v6
	v_add_u32_e32 v6, 0, v146
	ds_read_b128 v[26:29], v6
	ds_read_b128 v[30:33], v6 offset:4096
	v_lshlrev_b32_e32 v9, 3, v67
	v_add_u32_e32 v34, v40, v9
	v_or_b32_e32 v11, 0x200, v9
	v_add_u32_e32 v41, v40, v11
	v_or_b32_e32 v12, 0x400, v9
	s_waitcnt vmcnt(18)
	v_add_u32_e32 v42, v40, v12
	v_xor_b32_e32 v7, 1, v1
	v_cmp_lt_i32_e32 vcc, v7, v39
	v_xor_b32_e32 v8, 2, v1
	v_xor_b32_e32 v10, 4, v1
	v_cndmask_b32_e32 v7, v1, v7, vcc
	v_lshlrev_b32_e32 v7, 2, v7
	v_cmp_lt_i32_e32 vcc, v8, v39
	v_cmp_lt_i32_e64 s[0:1], v10, v39
	v_xor_b32_e32 v13, 8, v1
	v_cndmask_b32_e32 v8, v1, v8, vcc
	v_lshlrev_b32_e32 v8, 2, v8
	v_cndmask_b32_e64 v10, v1, v10, s[0:1]
	v_lshlrev_b32_e32 v10, 2, v10
	v_cmp_lt_i32_e64 s[0:1], v13, v39
	v_xor_b32_e32 v38, 16, v1
	v_cmp_eq_u32_e32 vcc, 0, v67
	v_cndmask_b32_e64 v13, v1, v13, s[0:1]
	v_lshlrev_b32_e32 v13, 2, v13
	v_cmp_lt_i32_e64 s[0:1], v38, v39
	s_waitcnt vmcnt(3) lgkmcnt(1)
	v_pk_mul_f32 v[28:29], v[4:5], v[28:29]
	v_pk_mul_f32 v[26:27], v[2:3], v[26:27]
	s_waitcnt lgkmcnt(0)
	v_mul_f32_e32 v31, v3, v31
	v_cvt_pk_bf16_f32 v26, v26, v27
	v_cvt_pk_bf16_f32 v27, v28, v29
	ds_write_b64 v34, v[26:27] offset:8192
	ds_read_b128 v[26:29], v6 offset:1024
	ds_read_b128 v[34:37], v6 offset:5120
	v_mul_f32_e32 v33, v5, v33
	v_fmac_f32_e32 v31, v2, v30
	v_fmac_f32_e32 v33, v4, v32
	v_add_f32_e32 v2, v31, v33
	v_add_f32_e32 v30, 0, v2
	s_waitcnt vmcnt(2) lgkmcnt(1)
	v_pk_mul_f32 v[2:3], v[16:17], v[28:29]
	v_pk_mul_f32 v[4:5], v[14:15], v[26:27]
	s_waitcnt lgkmcnt(0)
	v_mul_f32_e32 v31, v15, v35
	v_cvt_pk_bf16_f32 v4, v4, v5
	v_cvt_pk_bf16_f32 v5, v2, v3
	ds_write_b64 v41, v[4:5] offset:8192
	ds_read_b128 v[2:5], v6 offset:2048
	ds_read_b128 v[26:29], v6 offset:6144
	v_mul_f32_e32 v32, v17, v37
	v_fmac_f32_e32 v31, v14, v34
	v_fmac_f32_e32 v32, v16, v36
	s_waitcnt vmcnt(1) lgkmcnt(1)
	v_pk_mul_f32 v[4:5], v[20:21], v[4:5]
	v_pk_mul_f32 v[2:3], v[18:19], v[2:3]
	v_add_f32_e32 v14, v31, v32
	v_cvt_pk_bf16_f32 v2, v2, v3
	v_cvt_pk_bf16_f32 v3, v4, v5
	ds_write_b64 v42, v[2:3] offset:8192
	v_add_f32_e32 v30, v30, v14
	ds_read_b128 v[2:5], v6 offset:3072
	ds_read_b128 v[14:17], v6 offset:7168
	s_waitcnt lgkmcnt(3)
	v_mul_f32_e32 v27, v19, v27
	v_mul_f32_e32 v29, v21, v29
	v_fmac_f32_e32 v27, v18, v26
	v_fmac_f32_e32 v29, v20, v28
	s_waitcnt vmcnt(0) lgkmcnt(0)
	v_mul_f32_e32 v15, v23, v15
	v_mul_f32_e32 v17, v25, v17
	v_add_f32_e32 v18, v27, v29
	v_fmac_f32_e32 v15, v22, v14
	v_fmac_f32_e32 v17, v24, v16
	v_add_f32_e32 v18, v30, v18
	v_add_f32_e32 v14, v15, v17
	v_add_f32_e32 v14, v18, v14
	ds_bpermute_b32 v15, v7, v14
	v_xor_b32_e32 v16, 32, v1
	v_cndmask_b32_e64 v17, v1, v38, s[0:1]
	v_cmp_lt_i32_e64 s[0:1], v16, v39
	v_pk_mul_f32 v[4:5], v[24:25], v[4:5]
	s_waitcnt lgkmcnt(0)
	v_add_f32_e32 v14, v14, v15
	ds_bpermute_b32 v15, v8, v14
	v_pk_mul_f32 v[2:3], v[22:23], v[2:3]
	s_waitcnt lgkmcnt(0)
	v_add_f32_e32 v14, v14, v15
	ds_bpermute_b32 v15, v10, v14
	v_cvt_pk_bf16_f32 v2, v2, v3
	v_cvt_pk_bf16_f32 v3, v4, v5
	s_waitcnt lgkmcnt(0)
	v_add_f32_e32 v18, v14, v15
	ds_bpermute_b32 v19, v13, v18
	v_cndmask_b32_e64 v15, v1, v16, s[0:1]
	v_lshlrev_b32_e32 v14, 2, v17
	v_lshlrev_b32_e32 v15, 2, v15
	s_load_dwordx2 s[0:1], s[92:93], 0x30
	s_waitcnt lgkmcnt(0)
	v_add_f32_e32 v16, v18, v19
	ds_bpermute_b32 v17, v14, v16
	s_waitcnt lgkmcnt(0)
	v_add_f32_e32 v4, v16, v17
	ds_bpermute_b32 v5, v15, v4
	v_or_b32_e32 v16, 0x600, v9
	v_add_u32_e32 v17, v40, v16
	ds_write_b64 v17, v[2:3] offset:8192
	v_lshl_add_u64 v[2:3], v[68:69], 2, s[0:1]
	s_and_saveexec_b64 s[0:1], vcc
	s_cbranch_execz .LBB0_276
	global_load_dword v17, v[2:3], off
	s_waitcnt lgkmcnt(1)
	v_add_f32_e32 v4, v4, v5
	v_lshl_add_u32 v5, v68, 2, 0
	v_add_u32_e32 v5, 0x21190, v5
	s_waitcnt vmcnt(0)
	v_add_f32_e32 v4, v4, v17
	ds_write_b32 v5, v4
.LBB0_276:
	s_or_b64 exec, exec, s[0:1]
	v_add_u32_e32 v4, 8, v68
	s_waitcnt lgkmcnt(1)
	v_ashrrev_i32_e32 v5, 31, v4
	v_lshlrev_b32_e32 v17, 2, v67
	v_lshlrev_b64 v[18:19], 12, v[4:5]
	v_lshl_add_u64 v[18:19], s[18:19], 0, v[18:19]
	v_lshlrev_b32_e32 v146, 2, v17
	v_lshl_add_u64 v[30:31], v[18:19], 0, v[146:147]
	global_load_dwordx4 v[18:21], v[30:31], off nt
	global_load_dwordx4 v[22:25], v[30:31], off offset:1024 nt
	global_load_dwordx4 v[26:29], v[30:31], off offset:2048 nt
	s_nop 0
	global_load_dwordx4 v[30:33], v[30:31], off offset:3072 nt
	ds_read_b128 v[34:37], v6
	ds_read_b128 v[38:41], v6 offset:4096
	v_mul_lo_u32 v5, v4, s79
	v_add_u32_e32 v17, 0, v5
	v_add_u32_e32 v5, v17, v9
	v_add_u32_e32 v46, v17, v11
	v_add_u32_e32 v47, v17, v12
	s_waitcnt vmcnt(3) lgkmcnt(1)
	v_pk_mul_f32 v[36:37], v[20:21], v[36:37]
	v_pk_mul_f32 v[34:35], v[18:19], v[34:35]
	s_waitcnt lgkmcnt(0)
	v_mul_f32_e32 v39, v19, v39
	v_cvt_pk_bf16_f32 v34, v34, v35
	v_cvt_pk_bf16_f32 v35, v36, v37
	ds_write_b64 v5, v[34:35] offset:8192
	ds_read_b128 v[34:37], v6 offset:1024
	ds_read_b128 v[42:45], v6 offset:5120
	v_mul_f32_e32 v41, v21, v41
	v_fmac_f32_e32 v39, v18, v38
	v_fmac_f32_e32 v41, v20, v40
	s_waitcnt vmcnt(2) lgkmcnt(1)
	v_pk_mul_f32 v[18:19], v[24:25], v[36:37]
	v_pk_mul_f32 v[20:21], v[22:23], v[34:35]
	v_add_f32_e32 v5, v39, v41
	v_cvt_pk_bf16_f32 v20, v20, v21
	v_cvt_pk_bf16_f32 v21, v18, v19
	ds_write_b64 v46, v[20:21] offset:8192
	ds_read_b128 v[18:21], v6 offset:2048
	ds_read_b128 v[34:37], v6 offset:6144
	s_waitcnt lgkmcnt(3)
	v_mul_f32_e32 v38, v23, v43
	v_mul_f32_e32 v39, v25, v45
	v_fmac_f32_e32 v38, v22, v42
	s_waitcnt vmcnt(1) lgkmcnt(1)
	v_pk_mul_f32 v[20:21], v[28:29], v[20:21]
	v_pk_mul_f32 v[18:19], v[26:27], v[18:19]
	v_fmac_f32_e32 v39, v24, v44
	v_cvt_pk_bf16_f32 v18, v18, v19
	v_cvt_pk_bf16_f32 v19, v20, v21
	ds_write_b64 v47, v[18:19] offset:8192
	ds_read_b128 v[18:21], v6 offset:7168
	v_add_f32_e32 v5, 0, v5
	v_add_f32_e32 v22, v38, v39
	v_add_f32_e32 v5, v5, v22
	s_waitcnt lgkmcnt(2)
	v_mul_f32_e32 v22, v27, v35
	v_mul_f32_e32 v23, v29, v37
	v_fmac_f32_e32 v22, v26, v34
	v_fmac_f32_e32 v23, v28, v36
	v_add_f32_e32 v22, v22, v23
	v_add_f32_e32 v5, v5, v22
	ds_read_b128 v[22:25], v6 offset:3072
	s_waitcnt vmcnt(0) lgkmcnt(1)
	v_mul_f32_e32 v19, v31, v19
	v_mul_f32_e32 v21, v33, v21
	v_fmac_f32_e32 v19, v30, v18
	v_fmac_f32_e32 v21, v32, v20
	v_add_f32_e32 v18, v19, v21
	v_add_f32_e32 v5, v5, v18
	ds_bpermute_b32 v18, v7, v5
	s_waitcnt lgkmcnt(1)
	v_pk_mul_f32 v[20:21], v[32:33], v[24:25]
	v_pk_mul_f32 v[22:23], v[30:31], v[22:23]
	v_add_u32_e32 v19, v17, v16
	v_cvt_pk_bf16_f32 v22, v22, v23
	s_waitcnt lgkmcnt(0)
	v_add_f32_e32 v5, v5, v18
	ds_bpermute_b32 v18, v8, v5
	v_cvt_pk_bf16_f32 v23, v20, v21
	ds_write_b64 v19, v[22:23] offset:8192
	s_waitcnt lgkmcnt(1)
	v_add_f32_e32 v5, v5, v18
	ds_bpermute_b32 v18, v10, v5
	s_waitcnt lgkmcnt(0)
	v_add_f32_e32 v5, v5, v18
	ds_bpermute_b32 v18, v13, v5
	s_waitcnt lgkmcnt(0)
	v_add_f32_e32 v5, v5, v18
	ds_bpermute_b32 v18, v14, v5
	s_waitcnt lgkmcnt(0)
	v_add_f32_e32 v5, v5, v18
	ds_bpermute_b32 v18, v15, v5
	s_and_saveexec_b64 s[0:1], vcc
	s_cbranch_execz .LBB0_278
	global_load_dword v19, v[2:3], off offset:32
	s_waitcnt lgkmcnt(0)
	v_add_f32_e32 v5, v5, v18
	v_lshl_add_u32 v4, v4, 2, 0
	v_add_u32_e32 v4, 0x21190, v4
	s_waitcnt vmcnt(0)
	v_add_f32_e32 v5, v5, v19
	ds_write_b32 v4, v5
.LBB0_278:
	s_or_b64 exec, exec, s[0:1]
	v_add_u32_e32 v4, 16, v68
	v_ashrrev_i32_e32 v5, 31, v4
	s_waitcnt lgkmcnt(0)
	v_lshlrev_b64 v[18:19], 12, v[4:5]
	v_lshl_add_u64 v[18:19], s[18:19], 0, v[18:19]
	v_lshl_add_u64 v[30:31], v[18:19], 0, v[146:147]
	global_load_dwordx4 v[18:21], v[30:31], off nt
	global_load_dwordx4 v[22:25], v[30:31], off offset:1024 nt
	global_load_dwordx4 v[26:29], v[30:31], off offset:2048 nt
	s_nop 0
	global_load_dwordx4 v[30:33], v[30:31], off offset:3072 nt
	ds_read_b128 v[34:37], v6
	ds_read_b128 v[38:41], v6 offset:4096
	v_add_u32_e32 v17, 0x4080, v17
	v_add_u32_e32 v5, v17, v9
	v_add_u32_e32 v9, v17, v11
	v_add_u32_e32 v11, v17, v12
	s_waitcnt vmcnt(3) lgkmcnt(1)
	v_pk_mul_f32 v[36:37], v[20:21], v[36:37]
	v_pk_mul_f32 v[34:35], v[18:19], v[34:35]
	s_waitcnt lgkmcnt(0)
	v_mul_f32_e32 v12, v19, v39
	v_cvt_pk_bf16_f32 v34, v34, v35
	v_cvt_pk_bf16_f32 v35, v36, v37
	ds_write_b64 v5, v[34:35] offset:8192
	ds_read_b128 v[34:37], v6 offset:1024
	ds_read_b128 v[42:45], v6 offset:5120
	v_mul_f32_e32 v39, v21, v41
	v_fmac_f32_e32 v12, v18, v38
	v_fmac_f32_e32 v39, v20, v40
	s_waitcnt vmcnt(2) lgkmcnt(1)
	v_pk_mul_f32 v[18:19], v[24:25], v[36:37]
	v_pk_mul_f32 v[20:21], v[22:23], v[34:35]
	v_add_f32_e32 v5, v12, v39
	v_cvt_pk_bf16_f32 v20, v20, v21
	v_cvt_pk_bf16_f32 v21, v18, v19
	ds_write_b64 v9, v[20:21] offset:8192
	ds_read_b128 v[18:21], v6 offset:2048
	ds_read_b128 v[34:37], v6 offset:6144
	s_waitcnt lgkmcnt(3)
	v_mul_f32_e32 v12, v23, v43
	v_mul_f32_e32 v38, v25, v45
	v_fmac_f32_e32 v12, v22, v42
	s_waitcnt vmcnt(1) lgkmcnt(1)
	v_pk_mul_f32 v[20:21], v[28:29], v[20:21]
	v_pk_mul_f32 v[18:19], v[26:27], v[18:19]
	v_fmac_f32_e32 v38, v24, v44
	v_cvt_pk_bf16_f32 v18, v18, v19
	v_cvt_pk_bf16_f32 v19, v20, v21
	ds_write_b64 v11, v[18:19] offset:8192
	ds_read_b128 v[18:21], v6 offset:7168
	ds_read_b128 v[22:25], v6 offset:3072
	v_add_f32_e32 v5, 0, v5
	v_add_f32_e32 v9, v12, v38
	v_add_f32_e32 v5, v5, v9
	s_waitcnt lgkmcnt(3)
	v_mul_f32_e32 v9, v27, v35
	v_mul_f32_e32 v12, v29, v37
	v_fmac_f32_e32 v9, v26, v34
	v_fmac_f32_e32 v12, v28, v36
	v_add_f32_e32 v9, v9, v12
	v_add_f32_e32 v5, v5, v9
	s_waitcnt vmcnt(0) lgkmcnt(1)
	v_mul_f32_e32 v6, v31, v19
	v_mul_f32_e32 v9, v33, v21
	v_fmac_f32_e32 v6, v30, v18
	v_fmac_f32_e32 v9, v32, v20
	v_add_f32_e32 v6, v6, v9
	v_add_f32_e32 v5, v5, v6
	ds_bpermute_b32 v6, v7, v5
	v_add_u32_e32 v7, v17, v16
	s_waitcnt lgkmcnt(0)
	v_add_f32_e32 v5, v5, v6
	ds_bpermute_b32 v6, v8, v5
	v_pk_mul_f32 v[8:9], v[32:33], v[24:25]
	s_waitcnt lgkmcnt(0)
	v_add_f32_e32 v5, v5, v6
	ds_bpermute_b32 v6, v10, v5
	v_pk_mul_f32 v[10:11], v[30:31], v[22:23]
	s_waitcnt lgkmcnt(0)
	v_add_f32_e32 v5, v5, v6
	ds_bpermute_b32 v6, v13, v5
	v_cvt_pk_bf16_f32 v10, v10, v11
	v_cvt_pk_bf16_f32 v11, v8, v9
	ds_write_b64 v7, v[10:11] offset:8192
	s_waitcnt lgkmcnt(1)
	v_add_f32_e32 v5, v5, v6
	ds_bpermute_b32 v6, v14, v5
	s_waitcnt lgkmcnt(0)
	v_add_f32_e32 v5, v5, v6
	ds_bpermute_b32 v6, v15, v5
	s_and_saveexec_b64 s[0:1], vcc
	s_cbranch_execz .LBB0_280
	global_load_dword v2, v[2:3], off offset:64
	s_waitcnt lgkmcnt(0)
	v_add_f32_e32 v3, v5, v6
	v_lshl_add_u32 v4, v4, 2, 0
	s_waitcnt vmcnt(0)
	v_add_f32_e32 v2, v3, v2
	v_add_u32_e32 v3, 0x21190, v4
	ds_write_b32 v3, v2

.LBB0_282:
	s_or_b64 exec, exec, s[0:1]
	v_and_b32_e32 v2, -8, v66
	v_cmp_eq_u32_e32 vcc, 24, v2
	s_and_saveexec_b64 s[0:1], vcc
	v_lshl_add_u32 v2, v66, 2, 0
	v_add_u32_e32 v2, 0x21190, v2
	ds_write_b32 v2, v147
	s_or_b64 exec, exec, s[0:1]
	s_ashr_i32 s55, s54, 31
	s_lshl_b64 s[14:15], s[54:55], 20
	v_and_b32_e32 v69, 15, v66
	s_add_u32 s0, s16, s14
	v_lshlrev_b32_e32 v70, 7, v68
	s_addc_u32 s1, s17, s15
	v_lshlrev_b32_e32 v146, 12, v69
	v_ashrrev_i32_e32 v71, 31, v70
	v_lshl_add_u64 v[2:3], s[0:1], 0, v[146:147]
	v_lshlrev_b64 v[72:73], 2, v[70:71]
	v_lshlrev_b32_e32 v4, 1, v67
	v_lshl_add_u64 v[2:3], v[2:3], 0, v[72:73]
	v_and_b32_e32 v74, 0x60, v4
	v_mov_b32_e32 v75, v147
	v_lshl_add_u64 v[50:51], v[2:3], 0, v[74:75]
	s_waitcnt lgkmcnt(0)
	s_barrier
	global_load_dwordx4 v[2:5], v[50:51], off offset:16 nt
	global_load_dwordx4 v[6:9], v[50:51], off nt
	global_load_dwordx4 v[18:21], v[50:51], off offset:144 nt
	global_load_dwordx4 v[10:13], v[50:51], off offset:128 nt
	global_load_dwordx4 v[22:25], v[50:51], off offset:272 nt
	global_load_dwordx4 v[14:17], v[50:51], off offset:256 nt
	global_load_dwordx4 v[30:33], v[50:51], off offset:400 nt
	global_load_dwordx4 v[26:29], v[50:51], off offset:384 nt
	v_add_co_u32_e32 v54, vcc, s81, v50
	v_lshl_add_u64 v[38:39], v[50:51], 0, s[24:25]
	s_nop 0
	v_addc_co_u32_e32 v55, vcc, 0, v51, vcc
	v_lshl_add_u64 v[52:53], v[50:51], 0, s[26:27]
	v_lshl_add_u64 v[58:59], v[50:51], 0, s[28:29]
	v_lshl_add_u64 v[62:63], v[50:51], 0, s[30:31]
	global_load_dwordx4 v[34:37], v[54:55], off nt
	s_nop 0
	global_load_dwordx4 v[38:41], v[38:39], off offset:16 nt
	s_nop 0
	global_load_dwordx4 v[42:45], v[54:55], off offset:128 nt
	global_load_dwordx4 v[46:49], v[54:55], off offset:256 nt
	s_nop 0
	global_load_dwordx4 v[50:53], v[52:53], off offset:16 nt
	s_nop 0
	global_load_dwordx4 v[54:57], v[54:55], off offset:384 nt
	s_nop 0
	global_load_dwordx4 v[58:61], v[58:59], off offset:16 nt
	s_nop 0
	global_load_dwordx4 v[62:65], v[62:63], off offset:16 nt
	v_and_b32_e32 v75, 48, v66
	v_lshl_or_b32 v159, v68, 8, v75
	v_lshl_or_b32 v77, v68, 4, v69
	v_lshl_or_b32 v68, v68, 9, v74
	v_ashrrev_i32_e32 v74, 4, v66
	v_ashrrev_i32_e32 v66, 1, v66
	v_and_b32_e32 v66, 0xffffff80, v66
	v_and_b32_e32 v80, 15, v74
	v_add_u32_e32 v162, 0, v68
	v_lshlrev_b32_e32 v68, 2, v66
	v_lshlrev_b32_e32 v81, 2, v80
	v_or_b32_e32 v66, v66, v80
	v_add3_u32 v163, 0, v68, v81
	v_mul_lo_u32 v68, v66, s82
	v_lshlrev_b32_e32 v66, 2, v69
	v_add_u32_e32 v164, 0, v66
	v_cmp_gt_u32_e64 s[0:1], 16, v67
	v_and_b32_e32 v67, 48, v67
	v_add_u32_e32 v165, v164, v68
	v_add3_u32 v168, s83, v68, v66
	v_mul_lo_u32 v68, v77, s82
	v_lshl_add_u32 v161, v77, 2, 0
	v_add_u32_e32 v78, 0, v67
	v_add_u32_e32 v67, s83, v67
	v_add_u32_e32 v77, 0x4800, v68
	s_add_i32 s4, 0, 0x21190
	v_add_u32_e32 v171, v67, v68
	v_add_u32_e32 v172, v67, v77
	s_lshl_b64 s[56:57], s[54:55], 19
	v_lshlrev_b32_e32 v67, 11, v69
	v_min_u32_e32 v76, 8, v69
	v_mad_u32_u24 v160, v69, s79, 0
	v_mul_i32_i24_e32 v79, 0xfffff7f4, v69
	v_add_u32_e32 v167, s4, v66
	v_cmp_gt_u32_e64 s[4:5], 8, v69
	v_add_u32_e32 v169, v78, v68
	v_or3_b32 v68, s56, v67, v75
	v_mov_b32_e32 v69, s57
	v_lshlrev_b32_e32 v67, 1, v75
	v_lshl_add_u64 v[148:149], v[70:71], 1, v[68:69]
	v_or3_b32 v68, s14, v146, v67
	s_mul_i32 s14, s54, 0x6000
	v_mov_b32_e32 v69, s15
	s_mul_hi_i32 s13, s54, 0x6000
	s_add_u32 s14, s14, 0x1000c00
	v_lshl_add_u64 v[68:69], v[68:69], 0, v[72:73]
	s_addc_u32 s15, s13, 0
	v_lshl_add_u64 v[150:151], s[22:23], 0, v[68:69]
	v_mov_b64_e32 v[68:69], s[14:15]
	v_mad_u32_u24 v76, v76, s79, 0
	v_mad_i64_i32 v[68:69], s[14:15], v74, s80, v[68:69]
	v_mov_b32_e32 v67, v147
	v_add_u32_e32 v166, 0xf190, v165
	v_add_u32_e32 v170, v78, v77
	v_lshl_add_u64 v[152:153], v[68:69], 0, v[66:67]
	s_mov_b32 s13, -2
	v_add_u32_e32 v146, v160, v79
	v_add_u32_e32 v173, v76, v159
	s_branch .LBB0_286

.LBB0_286:
	v_add_co_u32_e32 v68, vcc, s84, v150
	v_lshl_add_u64 v[66:67], v[150:151], 0, s[34:35]
	s_nop 0
	v_addc_co_u32_e32 v69, vcc, -1, v151, vcc
	global_load_dwordx4 v[126:129], v[68:69], off nt
	global_load_dwordx4 v[122:125], v[66:67], off offset:16 nt
	v_add_co_u32_e32 v68, vcc, s85, v150
	v_lshl_add_u64 v[66:67], v[150:151], 0, s[36:37]
	s_nop 0
	v_addc_co_u32_e32 v69, vcc, -1, v151, vcc
	global_load_dwordx4 v[110:113], v[68:69], off offset:-3968 nt
	global_load_dwordx4 v[106:109], v[66:67], off offset:16 nt
	v_lshl_add_u64 v[66:67], v[150:151], 0, s[38:39]
	v_lshl_add_u64 v[70:71], v[150:151], 0, s[40:41]
	global_load_dwordx4 v[94:97], v[68:69], off offset:-3840 nt
	global_load_dwordx4 v[78:81], v[68:69], off offset:-3712 nt
	global_load_dwordx4 v[90:93], v[66:67], off offset:16 nt
	global_load_dwordx4 v[74:77], v[70:71], off offset:16 nt
	global_load_dwordx4 v[114:117], v[150:151], off offset:16 nt
	global_load_dwordx4 v[118:121], v[150:151], off nt
	global_load_dwordx4 v[98:101], v[150:151], off offset:144 nt
	global_load_dwordx4 v[102:105], v[150:151], off offset:128 nt
	global_load_dwordx4 v[82:85], v[150:151], off offset:272 nt
	global_load_dwordx4 v[86:89], v[150:151], off offset:256 nt
	global_load_dwordx4 v[66:69], v[150:151], off offset:400 nt
	global_load_dwordx4 v[70:73], v[150:151], off offset:384 nt
	s_waitcnt vmcnt(30)
	v_mul_f32_e32 v138, v7, v7
	v_mul_f32_e32 v139, v9, v9
	v_fmac_f32_e32 v138, v6, v6
	v_fmac_f32_e32 v139, v8, v8
	v_mul_f32_e32 v176, v3, v3
	v_add_u32_e32 v174, v160, v159
	v_add_f32_e32 v175, v138, v139
	v_fmac_f32_e32 v176, v2, v2
	ds_read_b128 v[130:133], v174 offset:8192
	ds_read_b128 v[134:137], v173 offset:41216
	ds_read_b128 v[142:145], v174 offset:8256
	v_add_f32_e32 v175, v176, v175
	ds_read_b128 v[176:179], v173 offset:41280
	v_cvt_pk_bf16_f32 v138, v6, v7
	v_cvt_pk_bf16_f32 v139, v8, v9
	v_cvt_pk_bf16_f32 v140, v2, v3
	v_cvt_pk_bf16_f32 v141, v4, v5
	s_waitcnt vmcnt(23)
	v_cvt_pk_bf16_f32 v180, v34, v35
	v_cvt_pk_bf16_f32 v181, v36, v37
	s_waitcnt vmcnt(22)
	v_cvt_pk_bf16_f32 v182, v38, v39
	v_cvt_pk_bf16_f32 v183, v40, v41
	s_waitcnt lgkmcnt(3)
	v_mfma_f32_16x16x32_bf16 v[154:157], v[130:133], v[138:141], 0
	v_mul_f32_e32 v184, v5, v5
	v_fmac_f32_e32 v184, v4, v4
	v_mul_f32_e32 v185, v19, v19
	s_waitcnt lgkmcnt(2)
	v_mfma_f32_16x16x32_bf16 v[138:141], v[134:137], v[138:141], 0
	v_add_f32_e32 v175, v184, v175
	v_fmac_f32_e32 v185, v18, v18
	v_mul_f32_e32 v189, v23, v23
	v_mfma_f32_16x16x32_bf16 v[130:133], v[130:133], v[180:183], 0
	v_fmac_f32_e32 v189, v22, v22
	v_mul_f32_e32 v193, v25, v25
	v_fmac_f32_e32 v193, v24, v24
	v_mfma_f32_16x16x32_bf16 v[134:137], v[134:137], v[180:183], 0
	v_mul_f32_e32 v180, v11, v11
	v_mul_f32_e32 v181, v13, v13
	v_fmac_f32_e32 v180, v10, v10
	v_fmac_f32_e32 v181, v12, v12
	v_add_f32_e32 v184, v180, v181
	v_cvt_pk_bf16_f32 v180, v10, v11
	v_cvt_pk_bf16_f32 v181, v12, v13
	v_cvt_pk_bf16_f32 v182, v18, v19
	v_cvt_pk_bf16_f32 v183, v20, v21
	v_add_f32_e32 v184, v185, v184
	v_mul_f32_e32 v185, v21, v21
	s_waitcnt lgkmcnt(1)
	v_mfma_f32_16x16x32_bf16 v[154:157], v[142:145], v[180:183], v[154:157]
	v_fmac_f32_e32 v185, v20, v20
	s_waitcnt lgkmcnt(0)
	v_mfma_f32_16x16x32_bf16 v[138:141], v[176:179], v[180:183], v[138:141]
	s_waitcnt vmcnt(21)
	v_cvt_pk_bf16_f32 v180, v42, v43
	v_cvt_pk_bf16_f32 v181, v44, v45
	s_waitcnt vmcnt(19)
	v_cvt_pk_bf16_f32 v182, v50, v51
	v_cvt_pk_bf16_f32 v183, v52, v53
	s_nop 1
	v_mfma_f32_16x16x32_bf16 v[130:133], v[142:145], v[180:183], v[130:133]
	v_add_f32_e32 v142, v185, v184
	v_add_f32_e32 v175, v142, v175
	v_mfma_f32_16x16x32_bf16 v[134:137], v[176:179], v[180:183], v[134:137]
	ds_read_b128 v[142:145], v174 offset:8320
	ds_read_b128 v[176:179], v173 offset:41344
	v_mul_f32_e32 v180, v15, v15
	v_mul_f32_e32 v181, v17, v17
	v_fmac_f32_e32 v180, v14, v14
	v_fmac_f32_e32 v181, v16, v16
	v_add_f32_e32 v188, v180, v181
	ds_read_b128 v[184:187], v174 offset:8384
	v_cvt_pk_bf16_f32 v180, v14, v15
	v_cvt_pk_bf16_f32 v181, v16, v17
	v_cvt_pk_bf16_f32 v182, v22, v23
	v_cvt_pk_bf16_f32 v183, v24, v25
	v_add_f32_e32 v192, v189, v188
	ds_read_b128 v[188:191], v173 offset:41408
	s_waitcnt lgkmcnt(3)
	v_mfma_f32_16x16x32_bf16 v[154:157], v[142:145], v[180:183], v[154:157]
	s_waitcnt lgkmcnt(2)
	v_mfma_f32_16x16x32_bf16 v[180:183], v[176:179], v[180:183], v[138:141]
	s_nop 2
	v_cvt_pk_bf16_f32 v138, v46, v47
	v_cvt_pk_bf16_f32 v139, v48, v49
	s_waitcnt vmcnt(17)
	v_cvt_pk_bf16_f32 v140, v58, v59
	v_cvt_pk_bf16_f32 v141, v60, v61
	s_nop 1
	v_mfma_f32_16x16x32_bf16 v[130:133], v[142:145], v[138:141], v[130:133]
	v_add_f32_e32 v142, v193, v192
	v_add_f32_e32 v175, v142, v175
	v_cvt_pk_bf16_f32 v142, v26, v27
	v_mfma_f32_16x16x32_bf16 v[134:137], v[176:179], v[138:141], v[134:137]
	v_mul_f32_e32 v138, v27, v27
	v_mul_f32_e32 v139, v29, v29
	v_fmac_f32_e32 v138, v26, v26
	v_fmac_f32_e32 v139, v28, v28
	v_mul_f32_e32 v177, v31, v31
	v_add_f32_e32 v176, v138, v139
	v_fmac_f32_e32 v177, v30, v30
	v_add_f32_e32 v176, v177, v176
	v_mul_f32_e32 v177, v33, v33
	v_fmac_f32_e32 v177, v32, v32
	v_cvt_pk_bf16_f32 v143, v28, v29
	v_cvt_pk_bf16_f32 v144, v30, v31
	v_cvt_pk_bf16_f32 v145, v32, v33
	v_add_f32_e32 v176, v177, v176
	v_add_f32_e32 v175, v176, v175
	s_waitcnt lgkmcnt(1)
	v_mfma_f32_16x16x32_bf16 v[138:141], v[184:187], v[142:145], v[154:157]
	s_nop 2
	v_cvt_pk_bf16_f32 v154, v54, v55
	v_cvt_pk_bf16_f32 v155, v56, v57
	s_waitcnt vmcnt(16)
	v_cvt_pk_bf16_f32 v156, v62, v63
	v_cvt_pk_bf16_f32 v157, v64, v65
	s_waitcnt lgkmcnt(0)
	v_mfma_f32_16x16x32_bf16 v[142:145], v[188:191], v[142:145], v[180:183]
	v_mfma_f32_16x16x32_bf16 v[130:133], v[184:187], v[154:157], v[130:133]
	v_mfma_f32_16x16x32_bf16 v[134:137], v[188:191], v[154:157], v[134:137]
	v_mov_b32_e32 v154, v175
	s_nop 1
	v_permlane16_swap_b32_e32 v175, v154
	v_add_f32_e32 v154, v175, v154
	v_mov_b32_e32 v155, v154
	s_nop 1
	v_permlane32_swap_b32_e32 v154, v155
	s_and_saveexec_b64 s[14:15], s[0:1]
	v_add_f32_e32 v154, v154, v155
	ds_write_b32 v161, v154 offset:59792
	s_or_b64 exec, exec, s[14:15]
	v_mul_f32_e32 v154, v35, v35
	v_mul_f32_e32 v155, v37, v37
	v_fmac_f32_e32 v154, v34, v34
	v_fmac_f32_e32 v155, v36, v36
	v_add_f32_e32 v154, v154, v155
	v_mul_f32_e32 v155, v39, v39
	v_fmac_f32_e32 v155, v38, v38
	v_add_f32_e32 v154, v155, v154
	v_mul_f32_e32 v155, v41, v41
	v_fmac_f32_e32 v155, v40, v40
	v_add_f32_e32 v154, v155, v154
	v_mul_f32_e32 v155, v43, v43
	v_mul_f32_e32 v156, v45, v45
	v_fmac_f32_e32 v155, v42, v42
	v_fmac_f32_e32 v156, v44, v44
	v_add_f32_e32 v155, v155, v156
	v_mul_f32_e32 v156, v51, v51
	v_fmac_f32_e32 v156, v50, v50
	v_add_f32_e32 v155, v156, v155
	v_mul_f32_e32 v156, v53, v53
	v_fmac_f32_e32 v156, v52, v52
	v_add_f32_e32 v155, v156, v155
	v_add_f32_e32 v154, v155, v154
	v_mul_f32_e32 v155, v47, v47
	v_mul_f32_e32 v156, v49, v49
	v_fmac_f32_e32 v155, v46, v46
	v_fmac_f32_e32 v156, v48, v48
	v_add_f32_e32 v155, v155, v156
	v_mul_f32_e32 v156, v59, v59
	v_fmac_f32_e32 v156, v58, v58
	v_add_f32_e32 v155, v156, v155
	v_mul_f32_e32 v156, v61, v61
	v_fmac_f32_e32 v156, v60, v60
	v_add_f32_e32 v155, v156, v155
	v_add_f32_e32 v154, v155, v154
	v_mul_f32_e32 v155, v55, v55
	v_mul_f32_e32 v156, v57, v57
	v_fmac_f32_e32 v155, v54, v54
	v_fmac_f32_e32 v156, v56, v56
	v_add_f32_e32 v155, v155, v156
	v_mul_f32_e32 v156, v63, v63
	v_fmac_f32_e32 v156, v62, v62
	v_add_f32_e32 v155, v156, v155
	v_mul_f32_e32 v156, v65, v65
	v_fmac_f32_e32 v156, v64, v64
	v_add_f32_e32 v155, v156, v155
	v_add_f32_e32 v154, v155, v154
	ds_write_b128 v169, v[138:141] offset:61840
	ds_write_b128 v169, v[142:145] offset:61904
	v_mov_b32_e32 v138, v154
	s_nop 1
	v_permlane16_swap_b32_e32 v154, v138
	v_add_f32_e32 v138, v154, v138
	v_mov_b32_e32 v139, v138
	s_nop 1
	v_permlane32_swap_b32_e32 v138, v139
	s_and_saveexec_b64 s[14:15], s[0:1]
	v_add_f32_e32 v138, v138, v139
	ds_write_b32 v161, v138 offset:60304
	s_or_b64 exec, exec, s[14:15]
	ds_write_b128 v170, v[130:133] offset:61840
	ds_write_b128 v170, v[134:137] offset:61904
	v_add_u32_e32 v136, 0xe800, v146
	s_waitcnt lgkmcnt(0)
	s_barrier
	ds_read2_b32 v[130:131], v136 offset0:100 offset1:116
	ds_read2_b32 v[132:133], v136 offset0:132 offset1:148
	ds_read2_b32 v[134:135], v136 offset0:164 offset1:180
	v_lshl_add_u64 v[154:155], s[96:97], 0, v[148:149]
	v_add_u32_e32 v175, 0xe800, v163
	s_waitcnt lgkmcnt(2)
	v_add_f32_e32 v130, 0, v130
	v_add_f32_e32 v137, v130, v131
	ds_read2_b32 v[130:131], v136 offset0:196 offset1:212
	s_waitcnt lgkmcnt(2)
	v_add_f32_e32 v132, v137, v132
	v_add_f32_e32 v132, v132, v133
	s_waitcnt lgkmcnt(1)
	v_add_f32_e32 v132, v132, v134
	v_add_f32_e32 v132, v132, v135
	s_waitcnt lgkmcnt(0)
	v_add_f32_e32 v130, v132, v130
	v_add_f32_e32 v132, v130, v131
	ds_read2_b32 v[130:131], v136 offset0:228 offset1:244
	v_fmamk_f32 v132, v132, 0x3a800000, v158
	v_add_u32_e32 v136, 0xec00, v146
	v_rsq_f32_e32 v156, v132
	ds_read2_b32 v[132:133], v136 offset0:4 offset1:20
	ds_read2_b32 v[134:135], v136 offset0:36 offset1:52
	s_waitcnt lgkmcnt(2)
	v_add_f32_e32 v130, 0, v130
	v_add_f32_e32 v137, v130, v131
	ds_read2_b32 v[130:131], v136 offset0:68 offset1:84
	s_waitcnt lgkmcnt(2)
	v_add_f32_e32 v132, v137, v132
	v_add_f32_e32 v132, v132, v133
	s_waitcnt lgkmcnt(1)
	v_add_f32_e32 v132, v132, v134
	v_add_f32_e32 v132, v132, v135
	s_waitcnt lgkmcnt(0)
	v_add_f32_e32 v130, v132, v130
	v_add_f32_e32 v130, v130, v131
	v_fmamk_f32 v130, v130, 0x3a800000, v158
	v_rsq_f32_e32 v180, v130
	ds_read_b128 v[130:133], v162 offset:4096
	ds_read_b128 v[134:137], v162
	ds_read_b128 v[138:141], v162 offset:16
	ds_read_b128 v[142:145], v162 offset:4112
	v_pk_mul_f32 v[176:177], v[6:7], v[156:157] op_sel_hi:[1,0]
	v_pk_mul_f32 v[178:179], v[8:9], v[156:157] op_sel_hi:[1,0]
	v_pk_mul_f32 v[182:183], v[2:3], v[156:157] op_sel_hi:[1,0]
	s_waitcnt lgkmcnt(2)
	v_pk_fma_f32 v[178:179], v[178:179], v[136:137], v[132:133]
	v_pk_fma_f32 v[176:177], v[176:177], v[134:135], v[130:131]
	v_pk_mul_f32 v[184:185], v[4:5], v[156:157] op_sel_hi:[1,0]
	s_waitcnt lgkmcnt(0)
	v_pk_fma_f32 v[182:183], v[182:183], v[138:139], v[142:143]
	v_pk_fma_f32 v[184:185], v[184:185], v[140:141], v[144:145]
	v_cvt_pk_bf16_f32 v176, v176, v177
	v_cvt_pk_bf16_f32 v177, v178, v179
	v_cvt_pk_bf16_f32 v178, v182, v183
	v_add_co_u32_e32 v182, vcc, s86, v154
	v_cvt_pk_bf16_f32 v179, v184, v185
	s_nop 0
	v_addc_co_u32_e32 v183, vcc, 0, v155, vcc
	global_store_dwordx4 v[182:183], v[176:179], off
	v_add_co_u32_e32 v184, vcc, s87, v154
	s_nop 0
	v_pk_mul_f32 v[176:177], v[34:35], v[180:181] op_sel_hi:[1,0]
	v_pk_mul_f32 v[178:179], v[36:37], v[180:181] op_sel_hi:[1,0]
	v_pk_fma_f32 v[130:131], v[134:135], v[176:177], v[130:131]
	v_pk_fma_f32 v[132:133], v[136:137], v[178:179], v[132:133]
	v_pk_mul_f32 v[134:135], v[38:39], v[180:181] op_sel_hi:[1,0]
	v_pk_mul_f32 v[136:137], v[40:41], v[180:181] op_sel_hi:[1,0]
	v_pk_fma_f32 v[134:135], v[138:139], v[134:135], v[142:143]
	v_pk_fma_f32 v[136:137], v[140:141], v[136:137], v[144:145]
	v_cvt_pk_bf16_f32 v130, v130, v131
	v_cvt_pk_bf16_f32 v131, v132, v133
	v_cvt_pk_bf16_f32 v132, v134, v135
	v_cvt_pk_bf16_f32 v133, v136, v137
	v_addc_co_u32_e32 v185, vcc, 0, v155, vcc
	global_store_dwordx4 v[184:185], v[130:133], off
	ds_read_b128 v[130:133], v162 offset:4224
	ds_read_b128 v[134:137], v162 offset:128
	ds_read_b128 v[138:141], v162 offset:144
	ds_read_b128 v[142:145], v162 offset:4240
	v_pk_mul_f32 v[176:177], v[10:11], v[156:157] op_sel_hi:[1,0]
	v_pk_mul_f32 v[178:179], v[12:13], v[156:157] op_sel_hi:[1,0]
	v_pk_mul_f32 v[186:187], v[18:19], v[156:157] op_sel_hi:[1,0]
	v_pk_mul_f32 v[188:189], v[20:21], v[156:157] op_sel_hi:[1,0]
	s_waitcnt lgkmcnt(2)
	v_pk_fma_f32 v[178:179], v[178:179], v[136:137], v[132:133]
	v_pk_fma_f32 v[176:177], v[176:177], v[134:135], v[130:131]
	s_waitcnt lgkmcnt(0)
	v_pk_fma_f32 v[188:189], v[188:189], v[140:141], v[144:145]
	v_pk_fma_f32 v[186:187], v[186:187], v[138:139], v[142:143]
	v_cvt_pk_bf16_f32 v176, v176, v177
	v_cvt_pk_bf16_f32 v177, v178, v179
	v_cvt_pk_bf16_f32 v178, v186, v187
	v_cvt_pk_bf16_f32 v179, v188, v189
	global_store_dwordx4 v[182:183], v[176:179], off offset:64
	v_pk_mul_f32 v[186:187], v[22:23], v[156:157] op_sel_hi:[1,0]
	v_pk_mul_f32 v[188:189], v[24:25], v[156:157] op_sel_hi:[1,0]
	v_pk_mul_f32 v[176:177], v[42:43], v[180:181] op_sel_hi:[1,0]
	v_pk_mul_f32 v[178:179], v[44:45], v[180:181] op_sel_hi:[1,0]
	v_pk_fma_f32 v[130:131], v[134:135], v[176:177], v[130:131]
	v_pk_fma_f32 v[132:133], v[136:137], v[178:179], v[132:133]
	v_pk_mul_f32 v[134:135], v[50:51], v[180:181] op_sel_hi:[1,0]
	v_pk_mul_f32 v[136:137], v[52:53], v[180:181] op_sel_hi:[1,0]
	v_pk_fma_f32 v[134:135], v[134:135], v[138:139], v[142:143]
	v_pk_fma_f32 v[136:137], v[136:137], v[140:141], v[144:145]
	v_cvt_pk_bf16_f32 v130, v130, v131
	v_cvt_pk_bf16_f32 v131, v132, v133
	v_cvt_pk_bf16_f32 v132, v134, v135
	v_cvt_pk_bf16_f32 v133, v136, v137
	global_store_dwordx4 v[184:185], v[130:133], off offset:64
	ds_read_b128 v[130:133], v162 offset:4352
	ds_read_b128 v[134:137], v162 offset:256
	ds_read_b128 v[138:141], v162 offset:272
	ds_read_b128 v[142:145], v162 offset:4368
	v_pk_mul_f32 v[176:177], v[14:15], v[156:157] op_sel_hi:[1,0]
	v_pk_mul_f32 v[178:179], v[16:17], v[156:157] op_sel_hi:[1,0]
	s_waitcnt lgkmcnt(2)
	v_pk_fma_f32 v[176:177], v[176:177], v[134:135], v[130:131]
	v_pk_fma_f32 v[178:179], v[178:179], v[136:137], v[132:133]
	s_waitcnt lgkmcnt(0)
	v_pk_fma_f32 v[188:189], v[188:189], v[140:141], v[144:145]
	v_pk_fma_f32 v[186:187], v[186:187], v[138:139], v[142:143]
	v_cvt_pk_bf16_f32 v176, v176, v177
	v_cvt_pk_bf16_f32 v177, v178, v179
	v_cvt_pk_bf16_f32 v178, v186, v187
	v_cvt_pk_bf16_f32 v179, v188, v189
	global_store_dwordx4 v[182:183], v[176:179], off offset:128
	v_pk_mul_f32 v[186:187], v[30:31], v[156:157] op_sel_hi:[1,0]
	s_nop 0
	v_pk_mul_f32 v[176:177], v[46:47], v[180:181] op_sel_hi:[1,0]
	v_pk_mul_f32 v[178:179], v[48:49], v[180:181] op_sel_hi:[1,0]
	v_pk_fma_f32 v[130:131], v[176:177], v[134:135], v[130:131]
	v_pk_fma_f32 v[132:133], v[178:179], v[136:137], v[132:133]
	v_pk_mul_f32 v[134:135], v[58:59], v[180:181] op_sel_hi:[1,0]
	v_pk_mul_f32 v[136:137], v[60:61], v[180:181] op_sel_hi:[1,0]
	v_pk_fma_f32 v[134:135], v[134:135], v[138:139], v[142:143]
	v_pk_fma_f32 v[136:137], v[136:137], v[140:141], v[144:145]
	v_cvt_pk_bf16_f32 v130, v130, v131
	v_cvt_pk_bf16_f32 v131, v132, v133
	v_cvt_pk_bf16_f32 v132, v134, v135
	v_cvt_pk_bf16_f32 v133, v136, v137
	global_store_dwordx4 v[184:185], v[130:133], off offset:128
	ds_read_b128 v[130:133], v162 offset:4480
	ds_read_b128 v[134:137], v162 offset:384
	ds_read_b128 v[138:141], v162 offset:400
	ds_read_b128 v[142:145], v162 offset:4496
	v_pk_mul_f32 v[176:177], v[26:27], v[156:157] op_sel_hi:[1,0]
	v_pk_mul_f32 v[178:179], v[28:29], v[156:157] op_sel_hi:[1,0]
	v_pk_mul_f32 v[156:157], v[32:33], v[156:157] op_sel_hi:[1,0]
	s_waitcnt lgkmcnt(2)
	v_pk_fma_f32 v[178:179], v[178:179], v[136:137], v[132:133]
	v_pk_fma_f32 v[176:177], v[176:177], v[134:135], v[130:131]
	s_waitcnt lgkmcnt(0)
	v_pk_fma_f32 v[156:157], v[156:157], v[140:141], v[144:145]
	v_pk_fma_f32 v[186:187], v[186:187], v[138:139], v[142:143]
	v_cvt_pk_bf16_f32 v176, v176, v177
	v_cvt_pk_bf16_f32 v177, v178, v179
	v_cvt_pk_bf16_f32 v178, v186, v187
	v_cvt_pk_bf16_f32 v179, v156, v157
	global_store_dwordx4 v[182:183], v[176:179], off offset:192
	v_pk_mul_f32 v[156:157], v[54:55], v[180:181] op_sel_hi:[1,0]
	s_nop 0
	v_pk_mul_f32 v[176:177], v[56:57], v[180:181] op_sel_hi:[1,0]
	s_nop 0
	v_pk_fma_f32 v[136:137], v[176:177], v[136:137], v[132:133]
	v_pk_fma_f32 v[132:133], v[156:157], v[134:135], v[130:131]
	v_pk_mul_f32 v[134:135], v[64:65], v[180:181] op_sel_hi:[1,0]
	ds_read2_b32 v[156:157], v175 offset0:100 offset1:116
	v_pk_fma_f32 v[140:141], v[134:135], v[140:141], v[144:145]
	v_add_u32_e32 v134, 0x90, v165
	ds_read2st64_b32 v[134:135], v134 offset0:241 offset1:250
	v_pk_mul_f32 v[130:131], v[62:63], v[180:181] op_sel_hi:[1,0]
	s_waitcnt lgkmcnt(1)
	v_add_f32_e32 v144, 0, v156
	v_pk_fma_f32 v[138:139], v[130:131], v[138:139], v[142:143]
	ds_read2_b32 v[130:131], v175 offset0:132 offset1:148
	ds_read2st64_b32 v[142:143], v166 offset0:18 offset1:27
	s_waitcnt lgkmcnt(2)
	v_add_f32_e32 v134, 0, v134
	v_add_f32_e32 v144, v144, v157
	v_add_f32_e32 v134, v134, v135
	s_waitcnt lgkmcnt(1)
	v_add_f32_e32 v130, v144, v130
	s_waitcnt lgkmcnt(0)
	v_add_f32_e32 v142, v134, v142
	ds_read2_b32 v[134:135], v175 offset0:164 offset1:180
	ds_read2st64_b32 v[144:145], v166 offset0:36 offset1:45
	v_add_f32_e32 v156, v130, v131
	ds_read2_b32 v[130:131], v175 offset0:196 offset1:212
	v_add_f32_e32 v142, v142, v143
	s_waitcnt lgkmcnt(2)
	v_add_f32_e32 v134, v156, v134
	v_add_f32_e32 v134, v134, v135
	s_waitcnt lgkmcnt(1)
	v_add_f32_e32 v142, v142, v144
	s_waitcnt lgkmcnt(0)
	v_add_f32_e32 v130, v134, v130
	ds_read2st64_b32 v[134:135], v166 offset0:54 offset1:63
	v_add_f32_e32 v130, v130, v131
	v_fmamk_f32 v130, v130, 0x3a800000, v158
	ds_read_b32 v131, v167
	v_rsq_f32_e32 v130, v130
	v_add_f32_e32 v142, v142, v145
	s_waitcnt lgkmcnt(1)
	v_add_f32_e32 v134, v142, v134
	v_add_f32_e32 v134, v134, v135
	s_waitcnt lgkmcnt(0)
	v_fmac_f32_e32 v131, v134, v130
	v_mul_f32_e32 v131, 0xbfb8aa3b, v131
	v_exp_f32_e32 v131, v131
	v_cvt_pk_bf16_f32 v132, v132, v133
	v_cvt_pk_bf16_f32 v133, v136, v137
	v_cvt_pk_bf16_f32 v134, v138, v139
	v_add_f32_e32 v131, 1.0, v131
	v_rcp_f32_e32 v131, v131
	v_cvt_pk_bf16_f32 v135, v140, v141
	v_lshl_add_u64 v[156:157], s[96:97], 0, v[152:153]
	global_store_dwordx4 v[184:185], v[132:135], off offset:192
	global_store_dword v[156:157], v131, off offset:-3072
	s_and_saveexec_b64 s[14:15], s[4:5]
	s_cbranch_execz .LBB0_292
	v_add_u32_e32 v131, 0xd0, v165
	ds_read2st64_b32 v[132:133], v131 offset0:241 offset1:250
	v_add_u32_e32 v131, 64, v166
	ds_read2st64_b32 v[134:135], v131 offset0:18 offset1:27
	ds_read2st64_b32 v[136:137], v131 offset0:36 offset1:45
	ds_read2st64_b32 v[138:139], v131 offset0:54 offset1:63
	s_waitcnt lgkmcnt(3)
	v_add_f32_e32 v131, 0, v132
	v_add_f32_e32 v131, v131, v133
	s_waitcnt lgkmcnt(2)
	v_add_f32_e32 v131, v131, v134
	v_add_f32_e32 v131, v131, v135
	ds_read_b32 v132, v167 offset:64
	s_waitcnt lgkmcnt(2)
	v_add_f32_e32 v131, v131, v136
	v_add_f32_e32 v131, v131, v137
	s_waitcnt lgkmcnt(1)
	v_add_f32_e32 v131, v131, v138
	v_add_f32_e32 v131, v131, v139
	s_waitcnt lgkmcnt(0)
	v_fmac_f32_e32 v132, v131, v130
	v_mul_f32_e32 v130, 0xbfb8aa3b, v132
	v_exp_f32_e32 v130, v130
	s_nop 0
	v_add_f32_e32 v130, 1.0, v130
	v_rcp_f32_e32 v130, v130
	global_store_dword v[156:157], v130, off offset:-3008
.LBB0_292:
	s_or_b64 exec, exec, s[14:15]
	s_add_i32 s14, s13, 3
	s_cmp_gt_u32 s14, 6
	s_cbranch_scc1 .LBB0_294
	v_add_co_u32_e32 v22, vcc, 0x10000, v150
	v_lshl_add_u64 v[2:3], v[150:151], 0, s[24:25]
	s_nop 0
	v_addc_co_u32_e32 v23, vcc, 0, v151, vcc
	v_add_co_u32_e32 v54, vcc, s88, v150
	v_lshl_add_u64 v[18:19], v[150:151], 0, s[26:27]
	v_lshl_add_u64 v[24:25], v[150:151], 0, s[28:29]
	v_lshl_add_u64 v[30:31], v[150:151], 0, s[30:31]
	v_lshl_add_u64 v[38:39], v[150:151], 0, s[42:43]
	v_addc_co_u32_e32 v55, vcc, 0, v151, vcc
	v_lshl_add_u64 v[50:51], v[150:151], 0, s[44:45]
	v_lshl_add_u64 v[58:59], v[150:151], 0, s[46:47]
	v_lshl_add_u64 v[62:63], v[150:151], 0, s[48:49]
	global_load_dwordx4 v[6:9], v[22:23], off nt
	s_nop 0
	global_load_dwordx4 v[2:5], v[2:3], off offset:16 nt
	s_nop 0
	global_load_dwordx4 v[10:13], v[22:23], off offset:128 nt
	global_load_dwordx4 v[14:17], v[22:23], off offset:256 nt
	s_nop 0
	global_load_dwordx4 v[18:21], v[18:19], off offset:16 nt
	s_nop 0
	global_load_dwordx4 v[26:29], v[22:23], off offset:384 nt
	s_nop 0
	global_load_dwordx4 v[22:25], v[24:25], off offset:16 nt
	s_nop 0
	global_load_dwordx4 v[30:33], v[30:31], off offset:16 nt
	s_nop 0
	global_load_dwordx4 v[34:37], v[54:55], off nt
	s_nop 0
	global_load_dwordx4 v[38:41], v[38:39], off offset:16 nt
	s_nop 0
	global_load_dwordx4 v[42:45], v[54:55], off offset:128 nt
	global_load_dwordx4 v[46:49], v[54:55], off offset:256 nt
	s_nop 0
	global_load_dwordx4 v[50:53], v[50:51], off offset:16 nt
	s_nop 0
	global_load_dwordx4 v[54:57], v[54:55], off offset:384 nt
	s_nop 0
	global_load_dwordx4 v[58:61], v[58:59], off offset:16 nt
	s_nop 0
	global_load_dwordx4 v[62:65], v[62:63], off offset:16 nt
